# v41 plus branch-GEMM merge epilogue: gate loads (g and g+4KiB) prefetched one row group ahead instead of two serialized HBM round trips per group half
# speedup vs baseline: 1.0063x; 1.0063x over previous
; __device__ __forceinline__ unsigned cvt_pk_bf16(float lo, float hi) { unsigned r; asm volatile("v_cvt_pk_bf16_f32 %0, %1, %2" : "=v"(r) : "v"(lo), "v"(hi)); return r; }
;     __device__ __forceinline__ void operator()(f32x4 (&acc)[2][2][4][2], const Unit& u, int wr, int wc, int fr, int fq) const {
;         const int row0 = u.pm * BM + wr * 64 + fr; const int col0 = u.pn * BM + wc * 32 + 8 * fq; const int br = u.seg;
; #pragma unroll
;         for (int ai = 0; ai < 2; ++ai)
; #pragma unroll
;             for (int m = 0; m < 4; ++m) { const size_t row = (size_t)(row0 + ai * HALF + m * 16);
; #pragma unroll
;                 for (int bj = 0; bj < 2; ++bj) { const int col = col0 + bj * HALF;
;                     const u32x4 g = *(const u32x4*)(PG + row * 6144 + br * D + col);
;                     float s[8] = {bflo(g[0]), bfhi(g[0]), bflo(g[1]), bfhi(g[1]), bflo(g[2]), bfhi(g[2]), bflo(g[3]), bfhi(g[3])};
;                     if (br < 2) { const u32x4 h = *(const u32x4*)(PG + row * 6144 + (br + 1) * D + col);
;                         const float d[8] = {bflo(h[0]), bfhi(h[0]), bflo(h[1]), bfhi(h[1]), bflo(h[2]), bfhi(h[2]), bflo(h[3]), bfhi(h[3])};
; #pragma unroll
;                         for (int j = 0; j < 8; ++j) s[j] = s[j] * __builtin_amdgcn_rcpf(fmaxf(d[j], 1e-30f)); }
;                     f32x4& v0 = acc[ai][bj][m][0]; f32x4& v1 = acc[ai][bj][m][1];
; #pragma unroll
;                     for (int j = 0; j < 4; ++j) { v0[j] *= s[j]; v1[j] *= s[4 + j]; }
;                     if (br == 2) { u32x4 w; w.x = cvt_pk_bf16(v0[0], v0[1]); w.y = cvt_pk_bf16(v0[2], v0[3]); w.z = cvt_pk_bf16(v1[0], v1[1]); w.w = cvt_pk_bf16(v1[2], v1[3]);
;                         *(u32x4*)(MG + row * D + col) = w; } } }
;     }
.LBB0_1607:
	v_lshl_add_u32 v156, s24, 8, v1
	s_lshl_b32 s26, s35, 11
	v_mov_b64_e32 v[130:131], s[6:7]
	s_movk_i32 s2, 0x3000
	v_lshl_or_b32 v154, s20, 8, v173
	s_ashr_i32 s27, s26, 31
	v_mad_i64_i32 v[130:131], s[2:3], v156, s2, v[130:131]
	v_lshl_add_u64 v[134:135], s[26:27], 1, v[130:131]
	v_ashrrev_i32_e32 v155, 31, v154
	v_lshl_add_u64 v[162:163], v[154:155], 1, v[134:135]
	v_mov_b64_e32 v[230:231], v[162:163]
	s_mov_b64 s[100:101], 0x1000
	v_lshl_add_u64 v[250:251], v[230:231], 0, s[100:101]
	global_load_dwordx4 v[180:183], v[230:231], off
	global_load_dwordx4 v[184:187], v[250:251], off
	global_load_dwordx4 v[188:191], v[230:231], off offset:256
	global_load_dwordx4 v[192:195], v[250:251], off offset:256
	s_mov_b64 s[100:101], 0x30000
	v_lshl_add_u64 v[248:249], v[230:231], 0, s[100:101]
	s_mov_b64 s[100:101], 0x1000
	v_lshl_add_u64 v[250:251], v[248:249], 0, s[100:101]
	global_load_dwordx4 v[196:199], v[248:249], off
	global_load_dwordx4 v[200:203], v[250:251], off
	global_load_dwordx4 v[204:207], v[248:249], off offset:256
	global_load_dwordx4 v[208:211], v[250:251], off offset:256
	s_nop 1
	s_cmp_lt_i32 s35, 2
	s_cselect_b64 s[28:29], -1, 0
	s_cmp_gt_i32 s35, 1
	s_cselect_b64 s[20:21], -1, 0
	s_add_i32 s24, s26, 0x800
	s_ashr_i32 s25, s24, 31
	s_and_b64 vcc, exec, s[20:21]
	v_lshl_add_u64 v[160:161], s[24:25], 1, v[130:131]
	s_waitcnt vmcnt(7)
	s_nop 1
	v_mov_b64_e32 v[168:169], v[180:181]
	v_mov_b64_e32 v[170:171], v[182:183]
	v_lshlrev_b32_e32 v166, 16, v168
	v_and_b32_e32 v167, 0xffff0000, v168
	v_lshlrev_b32_e32 v164, 16, v169
	v_and_b32_e32 v165, 0xffff0000, v169
	v_lshlrev_b32_e32 v168, 16, v170
	v_and_b32_e32 v169, 0xffff0000, v170
	v_lshlrev_b32_e32 v158, 16, v171
	v_and_b32_e32 v159, 0xffff0000, v171
	s_cbranch_vccnz .LBB0_1609
	v_lshl_add_u64 v[130:131], v[154:155], 1, v[160:161]
	s_nop 1
	s_waitcnt vmcnt(6)
	s_nop 1
	v_mov_b64_e32 v[176:177], v[184:185]
	v_mov_b64_e32 v[178:179], v[186:187]
	v_lshlrev_b32_e32 v130, 16, v176
	v_and_b32_e32 v131, 0xffff0000, v176
	v_max_f32_e32 v130, v130, v130
	v_max_f32_e32 v131, v131, v131
	v_max_f32_e32 v130, 0xda24260, v130
	v_max_f32_e32 v131, 0xda24260, v131
	v_rcp_f32_e32 v130, v130
	v_rcp_f32_e32 v131, v131
	v_lshlrev_b32_e32 v134, 16, v177
	v_and_b32_e32 v135, 0xffff0000, v177
	v_lshlrev_b32_e32 v140, 16, v178
	v_pk_mul_f32 v[166:167], v[130:131], v[166:167]
	v_max_f32_e32 v130, v134, v134
	v_max_f32_e32 v131, v135, v135
	v_max_f32_e32 v130, 0xda24260, v130
	v_max_f32_e32 v131, 0xda24260, v131
	v_rcp_f32_e32 v130, v130
	v_rcp_f32_e32 v131, v131
	v_and_b32_e32 v141, 0xffff0000, v178
	v_lshlrev_b32_e32 v142, 16, v179
	v_and_b32_e32 v143, 0xffff0000, v179
	v_pk_mul_f32 v[164:165], v[130:131], v[164:165]
	v_max_f32_e32 v130, v140, v140
	v_max_f32_e32 v131, v141, v141
	v_max_f32_e32 v130, 0xda24260, v130
	v_max_f32_e32 v131, 0xda24260, v131
	v_rcp_f32_e32 v130, v130
	v_rcp_f32_e32 v131, v131
	s_nop 0
	v_pk_mul_f32 v[168:169], v[130:131], v[168:169]
	v_max_f32_e32 v130, v142, v142
	v_max_f32_e32 v131, v143, v143
	v_max_f32_e32 v130, 0xda24260, v130
	v_max_f32_e32 v131, 0xda24260, v131
	v_rcp_f32_e32 v130, v130
	v_rcp_f32_e32 v131, v131
	s_nop 0
	v_pk_mul_f32 v[158:159], v[130:131], v[158:159]

; __device__ __forceinline__ unsigned cvt_pk_bf16(float lo, float hi) { unsigned r; asm volatile("v_cvt_pk_bf16_f32 %0, %1, %2" : "=v"(r) : "v"(lo), "v"(hi)); return r; }
;     __device__ __forceinline__ void operator()(f32x4 (&acc)[2][2][4][2], const Unit& u, int wr, int wc, int fr, int fq) const {
;         const int row0 = u.pm * BM + wr * 64 + fr; const int col0 = u.pn * BM + wc * 32 + 8 * fq; const int br = u.seg;
; #pragma unroll
;         for (int ai = 0; ai < 2; ++ai)
; #pragma unroll
;             for (int m = 0; m < 4; ++m) { const size_t row = (size_t)(row0 + ai * HALF + m * 16);
; #pragma unroll
;                 for (int bj = 0; bj < 2; ++bj) { const int col = col0 + bj * HALF;
;                     const u32x4 g = *(const u32x4*)(PG + row * 6144 + br * D + col);
;                     float s[8] = {bflo(g[0]), bfhi(g[0]), bflo(g[1]), bfhi(g[1]), bflo(g[2]), bfhi(g[2]), bflo(g[3]), bfhi(g[3])};
;                     if (br < 2) { const u32x4 h = *(const u32x4*)(PG + row * 6144 + (br + 1) * D + col);
;                         const float d[8] = {bflo(h[0]), bfhi(h[0]), bflo(h[1]), bfhi(h[1]), bflo(h[2]), bfhi(h[2]), bflo(h[3]), bfhi(h[3])};
; #pragma unroll
;                         for (int j = 0; j < 8; ++j) s[j] = s[j] * __builtin_amdgcn_rcpf(fmaxf(d[j], 1e-30f)); }
;                     f32x4& v0 = acc[ai][bj][m][0]; f32x4& v1 = acc[ai][bj][m][1];
; #pragma unroll
;                     for (int j = 0; j < 4; ++j) { v0[j] *= s[j]; v1[j] *= s[4 + j]; }
;                     if (br == 2) { u32x4 w; w.x = cvt_pk_bf16(v0[0], v0[1]); w.y = cvt_pk_bf16(v0[2], v0[3]); w.z = cvt_pk_bf16(v1[0], v1[1]); w.w = cvt_pk_bf16(v1[2], v1[3]);
;                         *(u32x4*)(MG + row * D + col) = w; } } }
;     }
.LBB0_1611:
	s_nop 1
	v_cndmask_b32_e64 v130, 0, 1, s[28:29]
	v_cmp_ne_u32_e64 s[44:45], 1, v130
	s_andn2_b64 vcc, exec, s[28:29]
	s_waitcnt vmcnt(5)
	s_nop 1
	v_mov_b64_e32 v[168:169], v[188:189]
	v_mov_b64_e32 v[170:171], v[190:191]
	v_lshlrev_b32_e32 v166, 16, v168
	v_and_b32_e32 v167, 0xffff0000, v168
	v_lshlrev_b32_e32 v164, 16, v169
	v_and_b32_e32 v165, 0xffff0000, v169
	v_lshlrev_b32_e32 v168, 16, v170
	v_and_b32_e32 v169, 0xffff0000, v170
	v_lshlrev_b32_e32 v162, 16, v171
	v_and_b32_e32 v163, 0xffff0000, v171
	s_cbranch_vccnz .LBB0_1613
	v_lshl_add_u64 v[130:131], v[154:155], 1, v[160:161]
	s_nop 1
	s_waitcnt vmcnt(4)
	s_nop 1
	v_mov_b64_e32 v[176:177], v[192:193]
	v_mov_b64_e32 v[178:179], v[194:195]
	v_lshlrev_b32_e32 v130, 16, v176
	v_and_b32_e32 v131, 0xffff0000, v176
	v_max_f32_e32 v130, v130, v130
	v_max_f32_e32 v131, v131, v131
	v_max_f32_e32 v130, 0xda24260, v130
	v_max_f32_e32 v131, 0xda24260, v131
	v_rcp_f32_e32 v130, v130
	v_rcp_f32_e32 v131, v131
	v_lshlrev_b32_e32 v134, 16, v177
	v_and_b32_e32 v135, 0xffff0000, v177
	v_lshlrev_b32_e32 v140, 16, v178
	v_pk_mul_f32 v[166:167], v[130:131], v[166:167]
	v_max_f32_e32 v130, v134, v134
	v_max_f32_e32 v131, v135, v135
	v_max_f32_e32 v130, 0xda24260, v130
	v_max_f32_e32 v131, 0xda24260, v131
	v_rcp_f32_e32 v130, v130
	v_rcp_f32_e32 v131, v131
	v_and_b32_e32 v141, 0xffff0000, v178
	v_lshlrev_b32_e32 v142, 16, v179
	v_and_b32_e32 v143, 0xffff0000, v179
	v_pk_mul_f32 v[164:165], v[130:131], v[164:165]
	v_max_f32_e32 v130, v140, v140
	v_max_f32_e32 v131, v141, v141
	v_max_f32_e32 v130, 0xda24260, v130
	v_max_f32_e32 v131, 0xda24260, v131
	v_rcp_f32_e32 v130, v130
	v_rcp_f32_e32 v131, v131
	s_nop 0
	v_pk_mul_f32 v[168:169], v[130:131], v[168:169]
	v_max_f32_e32 v130, v142, v142
	v_max_f32_e32 v131, v143, v143
	v_max_f32_e32 v130, 0xda24260, v130
	v_max_f32_e32 v131, 0xda24260, v131
	v_rcp_f32_e32 v130, v130
	v_rcp_f32_e32 v131, v131
	s_nop 0
	v_pk_mul_f32 v[162:163], v[130:131], v[162:163]

; __device__ __forceinline__ unsigned cvt_pk_bf16(float lo, float hi) { unsigned r; asm volatile("v_cvt_pk_bf16_f32 %0, %1, %2" : "=v"(r) : "v"(lo), "v"(hi)); return r; }
;     __device__ __forceinline__ void operator()(f32x4 (&acc)[2][2][4][2], const Unit& u, int wr, int wc, int fr, int fq) const {
;         const int row0 = u.pm * BM + wr * 64 + fr; const int col0 = u.pn * BM + wc * 32 + 8 * fq; const int br = u.seg;
; #pragma unroll
;         for (int ai = 0; ai < 2; ++ai)
; #pragma unroll
;             for (int m = 0; m < 4; ++m) { const size_t row = (size_t)(row0 + ai * HALF + m * 16);
; #pragma unroll
;                 for (int bj = 0; bj < 2; ++bj) { const int col = col0 + bj * HALF;
;                     const u32x4 g = *(const u32x4*)(PG + row * 6144 + br * D + col);
;                     float s[8] = {bflo(g[0]), bfhi(g[0]), bflo(g[1]), bfhi(g[1]), bflo(g[2]), bfhi(g[2]), bflo(g[3]), bfhi(g[3])};
;                     if (br < 2) { const u32x4 h = *(const u32x4*)(PG + row * 6144 + (br + 1) * D + col);
;                         const float d[8] = {bflo(h[0]), bfhi(h[0]), bflo(h[1]), bfhi(h[1]), bflo(h[2]), bfhi(h[2]), bflo(h[3]), bfhi(h[3])};
; #pragma unroll
;                         for (int j = 0; j < 8; ++j) s[j] = s[j] * __builtin_amdgcn_rcpf(fmaxf(d[j], 1e-30f)); }
;                     f32x4& v0 = acc[ai][bj][m][0]; f32x4& v1 = acc[ai][bj][m][1];
; #pragma unroll
;                     for (int j = 0; j < 4; ++j) { v0[j] *= s[j]; v1[j] *= s[4 + j]; }
;                     if (br == 2) { u32x4 w; w.x = cvt_pk_bf16(v0[0], v0[1]); w.y = cvt_pk_bf16(v0[2], v0[3]); w.z = cvt_pk_bf16(v1[0], v1[1]); w.w = cvt_pk_bf16(v1[2], v1[3]);
;                         *(u32x4*)(MG + row * D + col) = w; } } }
;     }
.LBB0_1615:
	v_or_b32_e32 v158, 16, v156
	v_mov_b64_e32 v[130:131], s[6:7]
	v_mad_i64_i32 v[130:131], s[2:3], v158, s13, v[130:131]
	v_lshl_add_u64 v[134:135], s[26:27], 1, v[130:131]
	v_lshl_add_u64 v[162:163], v[154:155], 1, v[134:135]
	s_mov_b64 s[100:101], 0x60000
	v_lshl_add_u64 v[248:249], v[230:231], 0, s[100:101]
	s_mov_b64 s[100:101], 0x1000
	v_lshl_add_u64 v[250:251], v[248:249], 0, s[100:101]
	global_load_dwordx4 v[180:183], v[248:249], off
	global_load_dwordx4 v[184:187], v[250:251], off
	global_load_dwordx4 v[188:191], v[248:249], off offset:256
	global_load_dwordx4 v[192:195], v[250:251], off offset:256
	s_nop 1
	s_and_b64 vcc, exec, s[44:45]
	v_lshl_add_u64 v[160:161], s[24:25], 1, v[130:131]
	s_waitcnt vmcnt(7)
	s_nop 1
	v_mov_b64_e32 v[176:177], v[196:197]
	v_mov_b64_e32 v[178:179], v[198:199]
	v_lshlrev_b32_e32 v168, 16, v176
	v_and_b32_e32 v169, 0xffff0000, v176
	v_lshlrev_b32_e32 v166, 16, v177
	v_and_b32_e32 v167, 0xffff0000, v177
	v_lshlrev_b32_e32 v170, 16, v178
	v_and_b32_e32 v171, 0xffff0000, v178
	v_lshlrev_b32_e32 v164, 16, v179
	v_and_b32_e32 v165, 0xffff0000, v179
	s_cbranch_vccnz .LBB0_1617
	v_lshl_add_u64 v[130:131], v[154:155], 1, v[160:161]
	s_nop 1
	s_waitcnt vmcnt(6)
	s_nop 1
	v_mov_b64_e32 v[176:177], v[200:201]
	v_mov_b64_e32 v[178:179], v[202:203]
	v_lshlrev_b32_e32 v130, 16, v176
	v_and_b32_e32 v131, 0xffff0000, v176
	v_max_f32_e32 v130, v130, v130
	v_max_f32_e32 v131, v131, v131
	v_max_f32_e32 v130, 0xda24260, v130
	v_max_f32_e32 v131, 0xda24260, v131
	v_rcp_f32_e32 v130, v130
	v_rcp_f32_e32 v131, v131
	v_lshlrev_b32_e32 v134, 16, v177
	v_and_b32_e32 v135, 0xffff0000, v177
	v_lshlrev_b32_e32 v140, 16, v178
	v_pk_mul_f32 v[168:169], v[130:131], v[168:169]
	v_max_f32_e32 v130, v134, v134
	v_max_f32_e32 v131, v135, v135
	v_max_f32_e32 v130, 0xda24260, v130
	v_max_f32_e32 v131, 0xda24260, v131
	v_rcp_f32_e32 v130, v130
	v_rcp_f32_e32 v131, v131
	v_and_b32_e32 v141, 0xffff0000, v178
	v_lshlrev_b32_e32 v142, 16, v179
	v_and_b32_e32 v143, 0xffff0000, v179
	v_pk_mul_f32 v[166:167], v[130:131], v[166:167]
	v_max_f32_e32 v130, v140, v140
	v_max_f32_e32 v131, v141, v141
	v_max_f32_e32 v130, 0xda24260, v130
	v_max_f32_e32 v131, 0xda24260, v131
	v_rcp_f32_e32 v130, v130
	v_rcp_f32_e32 v131, v131
	s_nop 0
	v_pk_mul_f32 v[170:171], v[130:131], v[170:171]
	v_max_f32_e32 v130, v142, v142
	v_max_f32_e32 v131, v143, v143
	v_max_f32_e32 v130, 0xda24260, v130
	v_max_f32_e32 v131, 0xda24260, v131
	v_rcp_f32_e32 v130, v130
	v_rcp_f32_e32 v131, v131
	s_nop 0
	v_pk_mul_f32 v[164:165], v[130:131], v[164:165]

; __device__ __forceinline__ unsigned cvt_pk_bf16(float lo, float hi) { unsigned r; asm volatile("v_cvt_pk_bf16_f32 %0, %1, %2" : "=v"(r) : "v"(lo), "v"(hi)); return r; }
;     __device__ __forceinline__ void operator()(f32x4 (&acc)[2][2][4][2], const Unit& u, int wr, int wc, int fr, int fq) const {
;         const int row0 = u.pm * BM + wr * 64 + fr; const int col0 = u.pn * BM + wc * 32 + 8 * fq; const int br = u.seg;
; #pragma unroll
;         for (int ai = 0; ai < 2; ++ai)
; #pragma unroll
;             for (int m = 0; m < 4; ++m) { const size_t row = (size_t)(row0 + ai * HALF + m * 16);
; #pragma unroll
;                 for (int bj = 0; bj < 2; ++bj) { const int col = col0 + bj * HALF;
;                     const u32x4 g = *(const u32x4*)(PG + row * 6144 + br * D + col);
;                     float s[8] = {bflo(g[0]), bfhi(g[0]), bflo(g[1]), bfhi(g[1]), bflo(g[2]), bfhi(g[2]), bflo(g[3]), bfhi(g[3])};
;                     if (br < 2) { const u32x4 h = *(const u32x4*)(PG + row * 6144 + (br + 1) * D + col);
;                         const float d[8] = {bflo(h[0]), bfhi(h[0]), bflo(h[1]), bfhi(h[1]), bflo(h[2]), bfhi(h[2]), bflo(h[3]), bfhi(h[3])};
; #pragma unroll
;                         for (int j = 0; j < 8; ++j) s[j] = s[j] * __builtin_amdgcn_rcpf(fmaxf(d[j], 1e-30f)); }
;                     f32x4& v0 = acc[ai][bj][m][0]; f32x4& v1 = acc[ai][bj][m][1];
; #pragma unroll
;                     for (int j = 0; j < 4; ++j) { v0[j] *= s[j]; v1[j] *= s[4 + j]; }
;                     if (br == 2) { u32x4 w; w.x = cvt_pk_bf16(v0[0], v0[1]); w.y = cvt_pk_bf16(v0[2], v0[3]); w.z = cvt_pk_bf16(v1[0], v1[1]); w.w = cvt_pk_bf16(v1[2], v1[3]);
;                         *(u32x4*)(MG + row * D + col) = w; } } }
;     }
.LBB0_1619:
	s_nop 1
	s_and_b64 vcc, exec, s[44:45]
	s_waitcnt vmcnt(5)
	s_nop 1
	v_mov_b64_e32 v[168:169], v[204:205]
	v_mov_b64_e32 v[170:171], v[206:207]
	v_lshlrev_b32_e32 v166, 16, v168
	v_and_b32_e32 v167, 0xffff0000, v168
	v_lshlrev_b32_e32 v164, 16, v169
	v_and_b32_e32 v165, 0xffff0000, v169
	v_lshlrev_b32_e32 v168, 16, v170
	v_and_b32_e32 v169, 0xffff0000, v170
	v_lshlrev_b32_e32 v162, 16, v171
	v_and_b32_e32 v163, 0xffff0000, v171
	s_cbranch_vccnz .LBB0_1621
	v_lshl_add_u64 v[130:131], v[154:155], 1, v[160:161]
	s_nop 1
	s_waitcnt vmcnt(4)
	s_nop 1
	v_mov_b64_e32 v[176:177], v[208:209]
	v_mov_b64_e32 v[178:179], v[210:211]
	v_lshlrev_b32_e32 v130, 16, v176
	v_and_b32_e32 v131, 0xffff0000, v176
	v_max_f32_e32 v130, v130, v130
	v_max_f32_e32 v131, v131, v131
	v_max_f32_e32 v130, 0xda24260, v130
	v_max_f32_e32 v131, 0xda24260, v131
	v_rcp_f32_e32 v130, v130
	v_rcp_f32_e32 v131, v131
	v_lshlrev_b32_e32 v134, 16, v177
	v_and_b32_e32 v135, 0xffff0000, v177
	v_lshlrev_b32_e32 v140, 16, v178
	v_pk_mul_f32 v[166:167], v[130:131], v[166:167]
	v_max_f32_e32 v130, v134, v134
	v_max_f32_e32 v131, v135, v135
	v_max_f32_e32 v130, 0xda24260, v130
	v_max_f32_e32 v131, 0xda24260, v131
	v_rcp_f32_e32 v130, v130
	v_rcp_f32_e32 v131, v131
	v_and_b32_e32 v141, 0xffff0000, v178
	v_lshlrev_b32_e32 v142, 16, v179
	v_and_b32_e32 v143, 0xffff0000, v179
	v_pk_mul_f32 v[164:165], v[130:131], v[164:165]
	v_max_f32_e32 v130, v140, v140
	v_max_f32_e32 v131, v141, v141
	v_max_f32_e32 v130, 0xda24260, v130
	v_max_f32_e32 v131, 0xda24260, v131
	v_rcp_f32_e32 v130, v130
	v_rcp_f32_e32 v131, v131
	s_nop 0
	v_pk_mul_f32 v[168:169], v[130:131], v[168:169]
	v_max_f32_e32 v130, v142, v142
	v_max_f32_e32 v131, v143, v143
	v_max_f32_e32 v130, 0xda24260, v130
	v_max_f32_e32 v131, 0xda24260, v131
	v_rcp_f32_e32 v130, v130
	v_rcp_f32_e32 v131, v131
	s_nop 0
	v_pk_mul_f32 v[162:163], v[130:131], v[162:163]

; __device__ __forceinline__ unsigned cvt_pk_bf16(float lo, float hi) { unsigned r; asm volatile("v_cvt_pk_bf16_f32 %0, %1, %2" : "=v"(r) : "v"(lo), "v"(hi)); return r; }
;     __device__ __forceinline__ void operator()(f32x4 (&acc)[2][2][4][2], const Unit& u, int wr, int wc, int fr, int fq) const {
;         const int row0 = u.pm * BM + wr * 64 + fr; const int col0 = u.pn * BM + wc * 32 + 8 * fq; const int br = u.seg;
; #pragma unroll
;         for (int ai = 0; ai < 2; ++ai)
; #pragma unroll
;             for (int m = 0; m < 4; ++m) { const size_t row = (size_t)(row0 + ai * HALF + m * 16);
; #pragma unroll
;                 for (int bj = 0; bj < 2; ++bj) { const int col = col0 + bj * HALF;
;                     const u32x4 g = *(const u32x4*)(PG + row * 6144 + br * D + col);
;                     float s[8] = {bflo(g[0]), bfhi(g[0]), bflo(g[1]), bfhi(g[1]), bflo(g[2]), bfhi(g[2]), bflo(g[3]), bfhi(g[3])};
;                     if (br < 2) { const u32x4 h = *(const u32x4*)(PG + row * 6144 + (br + 1) * D + col);
;                         const float d[8] = {bflo(h[0]), bfhi(h[0]), bflo(h[1]), bfhi(h[1]), bflo(h[2]), bfhi(h[2]), bflo(h[3]), bfhi(h[3])};
; #pragma unroll
;                         for (int j = 0; j < 8; ++j) s[j] = s[j] * __builtin_amdgcn_rcpf(fmaxf(d[j], 1e-30f)); }
;                     f32x4& v0 = acc[ai][bj][m][0]; f32x4& v1 = acc[ai][bj][m][1];
; #pragma unroll
;                     for (int j = 0; j < 4; ++j) { v0[j] *= s[j]; v1[j] *= s[4 + j]; }
;                     if (br == 2) { u32x4 w; w.x = cvt_pk_bf16(v0[0], v0[1]); w.y = cvt_pk_bf16(v0[2], v0[3]); w.z = cvt_pk_bf16(v1[0], v1[1]); w.w = cvt_pk_bf16(v1[2], v1[3]);
;                         *(u32x4*)(MG + row * D + col) = w; } } }
;     }
.LBB0_1623:
	v_or_b32_e32 v158, 32, v156
	v_mov_b64_e32 v[130:131], s[6:7]
	v_mad_i64_i32 v[130:131], s[2:3], v158, s13, v[130:131]
	v_lshl_add_u64 v[134:135], s[26:27], 1, v[130:131]
	v_lshl_add_u64 v[162:163], v[154:155], 1, v[134:135]
	s_mov_b64 s[100:101], 0x90000
	v_lshl_add_u64 v[248:249], v[230:231], 0, s[100:101]
	s_mov_b64 s[100:101], 0x1000
	v_lshl_add_u64 v[250:251], v[248:249], 0, s[100:101]
	global_load_dwordx4 v[196:199], v[248:249], off
	global_load_dwordx4 v[200:203], v[250:251], off
	global_load_dwordx4 v[204:207], v[248:249], off offset:256
	global_load_dwordx4 v[208:211], v[250:251], off offset:256
	s_nop 1
	s_and_b64 vcc, exec, s[44:45]
	v_lshl_add_u64 v[160:161], s[24:25], 1, v[130:131]
	s_waitcnt vmcnt(7)
	s_nop 1
	v_mov_b64_e32 v[176:177], v[180:181]
	v_mov_b64_e32 v[178:179], v[182:183]
	v_lshlrev_b32_e32 v168, 16, v176
	v_and_b32_e32 v169, 0xffff0000, v176
	v_lshlrev_b32_e32 v166, 16, v177
	v_and_b32_e32 v167, 0xffff0000, v177
	v_lshlrev_b32_e32 v170, 16, v178
	v_and_b32_e32 v171, 0xffff0000, v178
	v_lshlrev_b32_e32 v164, 16, v179
	v_and_b32_e32 v165, 0xffff0000, v179
	s_cbranch_vccnz .LBB0_1625
	v_lshl_add_u64 v[130:131], v[154:155], 1, v[160:161]
	s_nop 1
	s_waitcnt vmcnt(6)
	s_nop 1
	v_mov_b64_e32 v[176:177], v[184:185]
	v_mov_b64_e32 v[178:179], v[186:187]
	v_lshlrev_b32_e32 v130, 16, v176
	v_and_b32_e32 v131, 0xffff0000, v176
	v_max_f32_e32 v130, v130, v130
	v_max_f32_e32 v131, v131, v131
	v_max_f32_e32 v130, 0xda24260, v130
	v_max_f32_e32 v131, 0xda24260, v131
	v_rcp_f32_e32 v130, v130
	v_rcp_f32_e32 v131, v131
	v_lshlrev_b32_e32 v134, 16, v177
	v_and_b32_e32 v135, 0xffff0000, v177
	v_lshlrev_b32_e32 v140, 16, v178
	v_pk_mul_f32 v[168:169], v[130:131], v[168:169]
	v_max_f32_e32 v130, v134, v134
	v_max_f32_e32 v131, v135, v135
	v_max_f32_e32 v130, 0xda24260, v130
	v_max_f32_e32 v131, 0xda24260, v131
	v_rcp_f32_e32 v130, v130
	v_rcp_f32_e32 v131, v131
	v_and_b32_e32 v141, 0xffff0000, v178
	v_lshlrev_b32_e32 v142, 16, v179
	v_and_b32_e32 v143, 0xffff0000, v179
	v_pk_mul_f32 v[166:167], v[130:131], v[166:167]
	v_max_f32_e32 v130, v140, v140
	v_max_f32_e32 v131, v141, v141
	v_max_f32_e32 v130, 0xda24260, v130
	v_max_f32_e32 v131, 0xda24260, v131
	v_rcp_f32_e32 v130, v130
	v_rcp_f32_e32 v131, v131
	s_nop 0
	v_pk_mul_f32 v[170:171], v[130:131], v[170:171]
	v_max_f32_e32 v130, v142, v142
	v_max_f32_e32 v131, v143, v143
	v_max_f32_e32 v130, 0xda24260, v130
	v_max_f32_e32 v131, 0xda24260, v131
	v_rcp_f32_e32 v130, v130
	v_rcp_f32_e32 v131, v131
	s_nop 0
	v_pk_mul_f32 v[164:165], v[130:131], v[164:165]

; __device__ __forceinline__ unsigned cvt_pk_bf16(float lo, float hi) { unsigned r; asm volatile("v_cvt_pk_bf16_f32 %0, %1, %2" : "=v"(r) : "v"(lo), "v"(hi)); return r; }
;     __device__ __forceinline__ void operator()(f32x4 (&acc)[2][2][4][2], const Unit& u, int wr, int wc, int fr, int fq) const {
;         const int row0 = u.pm * BM + wr * 64 + fr; const int col0 = u.pn * BM + wc * 32 + 8 * fq; const int br = u.seg;
; #pragma unroll
;         for (int ai = 0; ai < 2; ++ai)
; #pragma unroll
;             for (int m = 0; m < 4; ++m) { const size_t row = (size_t)(row0 + ai * HALF + m * 16);
; #pragma unroll
;                 for (int bj = 0; bj < 2; ++bj) { const int col = col0 + bj * HALF;
;                     const u32x4 g = *(const u32x4*)(PG + row * 6144 + br * D + col);
;                     float s[8] = {bflo(g[0]), bfhi(g[0]), bflo(g[1]), bfhi(g[1]), bflo(g[2]), bfhi(g[2]), bflo(g[3]), bfhi(g[3])};
;                     if (br < 2) { const u32x4 h = *(const u32x4*)(PG + row * 6144 + (br + 1) * D + col);
;                         const float d[8] = {bflo(h[0]), bfhi(h[0]), bflo(h[1]), bfhi(h[1]), bflo(h[2]), bfhi(h[2]), bflo(h[3]), bfhi(h[3])};
; #pragma unroll
;                         for (int j = 0; j < 8; ++j) s[j] = s[j] * __builtin_amdgcn_rcpf(fmaxf(d[j], 1e-30f)); }
;                     f32x4& v0 = acc[ai][bj][m][0]; f32x4& v1 = acc[ai][bj][m][1];
; #pragma unroll
;                     for (int j = 0; j < 4; ++j) { v0[j] *= s[j]; v1[j] *= s[4 + j]; }
;                     if (br == 2) { u32x4 w; w.x = cvt_pk_bf16(v0[0], v0[1]); w.y = cvt_pk_bf16(v0[2], v0[3]); w.z = cvt_pk_bf16(v1[0], v1[1]); w.w = cvt_pk_bf16(v1[2], v1[3]);
;                         *(u32x4*)(MG + row * D + col) = w; } } }
;     }
.LBB0_1627:
	s_nop 1
	s_and_b64 vcc, exec, s[44:45]
	s_waitcnt vmcnt(5)
	s_nop 1
	v_mov_b64_e32 v[168:169], v[188:189]
	v_mov_b64_e32 v[170:171], v[190:191]
	v_lshlrev_b32_e32 v166, 16, v168
	v_and_b32_e32 v167, 0xffff0000, v168
	v_lshlrev_b32_e32 v164, 16, v169
	v_and_b32_e32 v165, 0xffff0000, v169
	v_lshlrev_b32_e32 v168, 16, v170
	v_and_b32_e32 v169, 0xffff0000, v170
	v_lshlrev_b32_e32 v162, 16, v171
	v_and_b32_e32 v163, 0xffff0000, v171
	s_cbranch_vccnz .LBB0_1629
	v_lshl_add_u64 v[130:131], v[154:155], 1, v[160:161]
	s_nop 1
	s_waitcnt vmcnt(4)
	s_nop 1
	v_mov_b64_e32 v[176:177], v[192:193]
	v_mov_b64_e32 v[178:179], v[194:195]
	v_lshlrev_b32_e32 v130, 16, v176
	v_and_b32_e32 v131, 0xffff0000, v176
	v_max_f32_e32 v130, v130, v130
	v_max_f32_e32 v131, v131, v131
	v_max_f32_e32 v130, 0xda24260, v130
	v_max_f32_e32 v131, 0xda24260, v131
	v_rcp_f32_e32 v130, v130
	v_rcp_f32_e32 v131, v131
	v_lshlrev_b32_e32 v134, 16, v177
	v_and_b32_e32 v135, 0xffff0000, v177
	v_lshlrev_b32_e32 v140, 16, v178
	v_pk_mul_f32 v[166:167], v[130:131], v[166:167]
	v_max_f32_e32 v130, v134, v134
	v_max_f32_e32 v131, v135, v135
	v_max_f32_e32 v130, 0xda24260, v130
	v_max_f32_e32 v131, 0xda24260, v131
	v_rcp_f32_e32 v130, v130
	v_rcp_f32_e32 v131, v131
	v_and_b32_e32 v141, 0xffff0000, v178
	v_lshlrev_b32_e32 v142, 16, v179
	v_and_b32_e32 v143, 0xffff0000, v179
	v_pk_mul_f32 v[164:165], v[130:131], v[164:165]
	v_max_f32_e32 v130, v140, v140
	v_max_f32_e32 v131, v141, v141
	v_max_f32_e32 v130, 0xda24260, v130
	v_max_f32_e32 v131, 0xda24260, v131
	v_rcp_f32_e32 v130, v130
	v_rcp_f32_e32 v131, v131
	s_nop 0
	v_pk_mul_f32 v[168:169], v[130:131], v[168:169]
	v_max_f32_e32 v130, v142, v142
	v_max_f32_e32 v131, v143, v143
	v_max_f32_e32 v130, 0xda24260, v130
	v_max_f32_e32 v131, 0xda24260, v131
	v_rcp_f32_e32 v130, v130
	v_rcp_f32_e32 v131, v131
	s_nop 0
	v_pk_mul_f32 v[162:163], v[130:131], v[162:163]

; __device__ __forceinline__ unsigned cvt_pk_bf16(float lo, float hi) { unsigned r; asm volatile("v_cvt_pk_bf16_f32 %0, %1, %2" : "=v"(r) : "v"(lo), "v"(hi)); return r; }
;     __device__ __forceinline__ void operator()(f32x4 (&acc)[2][2][4][2], const Unit& u, int wr, int wc, int fr, int fq) const {
;         const int row0 = u.pm * BM + wr * 64 + fr; const int col0 = u.pn * BM + wc * 32 + 8 * fq; const int br = u.seg;
; #pragma unroll
;         for (int ai = 0; ai < 2; ++ai)
; #pragma unroll
;             for (int m = 0; m < 4; ++m) { const size_t row = (size_t)(row0 + ai * HALF + m * 16);
; #pragma unroll
;                 for (int bj = 0; bj < 2; ++bj) { const int col = col0 + bj * HALF;
;                     const u32x4 g = *(const u32x4*)(PG + row * 6144 + br * D + col);
;                     float s[8] = {bflo(g[0]), bfhi(g[0]), bflo(g[1]), bfhi(g[1]), bflo(g[2]), bfhi(g[2]), bflo(g[3]), bfhi(g[3])};
;                     if (br < 2) { const u32x4 h = *(const u32x4*)(PG + row * 6144 + (br + 1) * D + col);
;                         const float d[8] = {bflo(h[0]), bfhi(h[0]), bflo(h[1]), bfhi(h[1]), bflo(h[2]), bfhi(h[2]), bflo(h[3]), bfhi(h[3])};
; #pragma unroll
;                         for (int j = 0; j < 8; ++j) s[j] = s[j] * __builtin_amdgcn_rcpf(fmaxf(d[j], 1e-30f)); }
;                     f32x4& v0 = acc[ai][bj][m][0]; f32x4& v1 = acc[ai][bj][m][1];
; #pragma unroll
;                     for (int j = 0; j < 4; ++j) { v0[j] *= s[j]; v1[j] *= s[4 + j]; }
;                     if (br == 2) { u32x4 w; w.x = cvt_pk_bf16(v0[0], v0[1]); w.y = cvt_pk_bf16(v0[2], v0[3]); w.z = cvt_pk_bf16(v1[0], v1[1]); w.w = cvt_pk_bf16(v1[2], v1[3]);
;                         *(u32x4*)(MG + row * D + col) = w; } } }
;     }
.LBB0_1631:
	v_or_b32_e32 v158, 48, v156
	v_mov_b64_e32 v[130:131], s[6:7]
	v_mad_i64_i32 v[130:131], s[2:3], v158, s13, v[130:131]
	v_lshl_add_u64 v[134:135], s[26:27], 1, v[130:131]
	v_lshl_add_u64 v[162:163], v[154:155], 1, v[134:135]
	s_mov_b64 s[100:101], 0x180000
	v_lshl_add_u64 v[248:249], v[230:231], 0, s[100:101]
	s_mov_b64 s[100:101], 0x1000
	v_lshl_add_u64 v[250:251], v[248:249], 0, s[100:101]
	global_load_dwordx4 v[180:183], v[248:249], off
	global_load_dwordx4 v[184:187], v[250:251], off
	global_load_dwordx4 v[188:191], v[248:249], off offset:256
	global_load_dwordx4 v[192:195], v[250:251], off offset:256
	s_nop 1
	s_and_b64 vcc, exec, s[44:45]
	v_lshl_add_u64 v[160:161], s[24:25], 1, v[130:131]
	s_waitcnt vmcnt(7)
	s_nop 1
	v_mov_b64_e32 v[176:177], v[196:197]
	v_mov_b64_e32 v[178:179], v[198:199]
	v_lshlrev_b32_e32 v168, 16, v176
	v_and_b32_e32 v169, 0xffff0000, v176
	v_lshlrev_b32_e32 v166, 16, v177
	v_and_b32_e32 v167, 0xffff0000, v177
	v_lshlrev_b32_e32 v170, 16, v178
	v_and_b32_e32 v171, 0xffff0000, v178
	v_lshlrev_b32_e32 v164, 16, v179
	v_and_b32_e32 v165, 0xffff0000, v179
	s_cbranch_vccnz .LBB0_1633
	v_lshl_add_u64 v[130:131], v[154:155], 1, v[160:161]
	s_nop 1
	s_waitcnt vmcnt(6)
	s_nop 1
	v_mov_b64_e32 v[176:177], v[200:201]
	v_mov_b64_e32 v[178:179], v[202:203]
	v_lshlrev_b32_e32 v130, 16, v176
	v_and_b32_e32 v131, 0xffff0000, v176
	v_max_f32_e32 v130, v130, v130
	v_max_f32_e32 v131, v131, v131
	v_max_f32_e32 v130, 0xda24260, v130
	v_max_f32_e32 v131, 0xda24260, v131
	v_rcp_f32_e32 v130, v130
	v_rcp_f32_e32 v131, v131
	v_lshlrev_b32_e32 v134, 16, v177
	v_and_b32_e32 v135, 0xffff0000, v177
	v_lshlrev_b32_e32 v140, 16, v178
	v_pk_mul_f32 v[168:169], v[130:131], v[168:169]
	v_max_f32_e32 v130, v134, v134
	v_max_f32_e32 v131, v135, v135
	v_max_f32_e32 v130, 0xda24260, v130
	v_max_f32_e32 v131, 0xda24260, v131
	v_rcp_f32_e32 v130, v130
	v_rcp_f32_e32 v131, v131
	v_and_b32_e32 v141, 0xffff0000, v178
	v_lshlrev_b32_e32 v142, 16, v179
	v_and_b32_e32 v143, 0xffff0000, v179
	v_pk_mul_f32 v[166:167], v[130:131], v[166:167]
	v_max_f32_e32 v130, v140, v140
	v_max_f32_e32 v131, v141, v141
	v_max_f32_e32 v130, 0xda24260, v130
	v_max_f32_e32 v131, 0xda24260, v131
	v_rcp_f32_e32 v130, v130
	v_rcp_f32_e32 v131, v131
	s_nop 0
	v_pk_mul_f32 v[170:171], v[130:131], v[170:171]
	v_max_f32_e32 v130, v142, v142
	v_max_f32_e32 v131, v143, v143
	v_max_f32_e32 v130, 0xda24260, v130
	v_max_f32_e32 v131, 0xda24260, v131
	v_rcp_f32_e32 v130, v130
	v_rcp_f32_e32 v131, v131
	s_nop 0
	v_pk_mul_f32 v[164:165], v[130:131], v[164:165]

; __device__ __forceinline__ unsigned cvt_pk_bf16(float lo, float hi) { unsigned r; asm volatile("v_cvt_pk_bf16_f32 %0, %1, %2" : "=v"(r) : "v"(lo), "v"(hi)); return r; }
;     __device__ __forceinline__ void operator()(f32x4 (&acc)[2][2][4][2], const Unit& u, int wr, int wc, int fr, int fq) const {
;         const int row0 = u.pm * BM + wr * 64 + fr; const int col0 = u.pn * BM + wc * 32 + 8 * fq; const int br = u.seg;
; #pragma unroll
;         for (int ai = 0; ai < 2; ++ai)
; #pragma unroll
;             for (int m = 0; m < 4; ++m) { const size_t row = (size_t)(row0 + ai * HALF + m * 16);
; #pragma unroll
;                 for (int bj = 0; bj < 2; ++bj) { const int col = col0 + bj * HALF;
;                     const u32x4 g = *(const u32x4*)(PG + row * 6144 + br * D + col);
;                     float s[8] = {bflo(g[0]), bfhi(g[0]), bflo(g[1]), bfhi(g[1]), bflo(g[2]), bfhi(g[2]), bflo(g[3]), bfhi(g[3])};
;                     if (br < 2) { const u32x4 h = *(const u32x4*)(PG + row * 6144 + (br + 1) * D + col);
;                         const float d[8] = {bflo(h[0]), bfhi(h[0]), bflo(h[1]), bfhi(h[1]), bflo(h[2]), bfhi(h[2]), bflo(h[3]), bfhi(h[3])};
; #pragma unroll
;                         for (int j = 0; j < 8; ++j) s[j] = s[j] * __builtin_amdgcn_rcpf(fmaxf(d[j], 1e-30f)); }
;                     f32x4& v0 = acc[ai][bj][m][0]; f32x4& v1 = acc[ai][bj][m][1];
; #pragma unroll
;                     for (int j = 0; j < 4; ++j) { v0[j] *= s[j]; v1[j] *= s[4 + j]; }
;                     if (br == 2) { u32x4 w; w.x = cvt_pk_bf16(v0[0], v0[1]); w.y = cvt_pk_bf16(v0[2], v0[3]); w.z = cvt_pk_bf16(v1[0], v1[1]); w.w = cvt_pk_bf16(v1[2], v1[3]);
;                         *(u32x4*)(MG + row * D + col) = w; } } }
;     }
.LBB0_1639:
	v_add_u32_e32 v158, 0x80, v156
	v_mov_b64_e32 v[130:131], s[6:7]
	v_mad_i64_i32 v[130:131], s[2:3], v158, s13, v[130:131]
	v_lshl_add_u64 v[134:135], s[26:27], 1, v[130:131]
	v_lshl_add_u64 v[162:163], v[154:155], 1, v[134:135]
	s_mov_b64 s[100:101], 0x1b0000
	v_lshl_add_u64 v[248:249], v[230:231], 0, s[100:101]
	s_mov_b64 s[100:101], 0x1000
	v_lshl_add_u64 v[250:251], v[248:249], 0, s[100:101]
	global_load_dwordx4 v[196:199], v[248:249], off
	global_load_dwordx4 v[200:203], v[250:251], off
	global_load_dwordx4 v[204:207], v[248:249], off offset:256
	global_load_dwordx4 v[208:211], v[250:251], off offset:256
	s_nop 1
	s_and_b64 vcc, exec, s[44:45]
	v_lshl_add_u64 v[160:161], s[24:25], 1, v[130:131]
	s_waitcnt vmcnt(7)
	s_nop 1
	v_mov_b64_e32 v[176:177], v[180:181]
	v_mov_b64_e32 v[178:179], v[182:183]
	v_lshlrev_b32_e32 v168, 16, v176
	v_and_b32_e32 v169, 0xffff0000, v176
	v_lshlrev_b32_e32 v166, 16, v177
	v_and_b32_e32 v167, 0xffff0000, v177
	v_lshlrev_b32_e32 v170, 16, v178
	v_and_b32_e32 v171, 0xffff0000, v178
	v_lshlrev_b32_e32 v164, 16, v179
	v_and_b32_e32 v165, 0xffff0000, v179
	s_cbranch_vccnz .LBB0_1641
	v_lshl_add_u64 v[130:131], v[154:155], 1, v[160:161]
	s_nop 1
	s_waitcnt vmcnt(6)
	s_nop 1
	v_mov_b64_e32 v[176:177], v[184:185]
	v_mov_b64_e32 v[178:179], v[186:187]
	v_lshlrev_b32_e32 v130, 16, v176
	v_and_b32_e32 v131, 0xffff0000, v176
	v_max_f32_e32 v130, v130, v130
	v_max_f32_e32 v131, v131, v131
	v_max_f32_e32 v130, 0xda24260, v130
	v_max_f32_e32 v131, 0xda24260, v131
	v_rcp_f32_e32 v130, v130
	v_rcp_f32_e32 v131, v131
	v_lshlrev_b32_e32 v134, 16, v177
	v_and_b32_e32 v135, 0xffff0000, v177
	v_lshlrev_b32_e32 v140, 16, v178
	v_pk_mul_f32 v[168:169], v[130:131], v[168:169]
	v_max_f32_e32 v130, v134, v134
	v_max_f32_e32 v131, v135, v135
	v_max_f32_e32 v130, 0xda24260, v130
	v_max_f32_e32 v131, 0xda24260, v131
	v_rcp_f32_e32 v130, v130
	v_rcp_f32_e32 v131, v131
	v_and_b32_e32 v141, 0xffff0000, v178
	v_lshlrev_b32_e32 v142, 16, v179
	v_and_b32_e32 v143, 0xffff0000, v179
	v_pk_mul_f32 v[166:167], v[130:131], v[166:167]
	v_max_f32_e32 v130, v140, v140
	v_max_f32_e32 v131, v141, v141
	v_max_f32_e32 v130, 0xda24260, v130
	v_max_f32_e32 v131, 0xda24260, v131
	v_rcp_f32_e32 v130, v130
	v_rcp_f32_e32 v131, v131
	s_nop 0
	v_pk_mul_f32 v[170:171], v[130:131], v[170:171]
	v_max_f32_e32 v130, v142, v142
	v_max_f32_e32 v131, v143, v143
	v_max_f32_e32 v130, 0xda24260, v130
	v_max_f32_e32 v131, 0xda24260, v131
	v_rcp_f32_e32 v130, v130
	v_rcp_f32_e32 v131, v131
	s_nop 0
	v_pk_mul_f32 v[164:165], v[130:131], v[164:165]

; __device__ __forceinline__ unsigned cvt_pk_bf16(float lo, float hi) { unsigned r; asm volatile("v_cvt_pk_bf16_f32 %0, %1, %2" : "=v"(r) : "v"(lo), "v"(hi)); return r; }
;     __device__ __forceinline__ void operator()(f32x4 (&acc)[2][2][4][2], const Unit& u, int wr, int wc, int fr, int fq) const {
;         const int row0 = u.pm * BM + wr * 64 + fr; const int col0 = u.pn * BM + wc * 32 + 8 * fq; const int br = u.seg;
; #pragma unroll
;         for (int ai = 0; ai < 2; ++ai)
; #pragma unroll
;             for (int m = 0; m < 4; ++m) { const size_t row = (size_t)(row0 + ai * HALF + m * 16);
; #pragma unroll
;                 for (int bj = 0; bj < 2; ++bj) { const int col = col0 + bj * HALF;
;                     const u32x4 g = *(const u32x4*)(PG + row * 6144 + br * D + col);
;                     float s[8] = {bflo(g[0]), bfhi(g[0]), bflo(g[1]), bfhi(g[1]), bflo(g[2]), bfhi(g[2]), bflo(g[3]), bfhi(g[3])};
;                     if (br < 2) { const u32x4 h = *(const u32x4*)(PG + row * 6144 + (br + 1) * D + col);
;                         const float d[8] = {bflo(h[0]), bfhi(h[0]), bflo(h[1]), bfhi(h[1]), bflo(h[2]), bfhi(h[2]), bflo(h[3]), bfhi(h[3])};
; #pragma unroll
;                         for (int j = 0; j < 8; ++j) s[j] = s[j] * __builtin_amdgcn_rcpf(fmaxf(d[j], 1e-30f)); }
;                     f32x4& v0 = acc[ai][bj][m][0]; f32x4& v1 = acc[ai][bj][m][1];
; #pragma unroll
;                     for (int j = 0; j < 4; ++j) { v0[j] *= s[j]; v1[j] *= s[4 + j]; }
;                     if (br == 2) { u32x4 w; w.x = cvt_pk_bf16(v0[0], v0[1]); w.y = cvt_pk_bf16(v0[2], v0[3]); w.z = cvt_pk_bf16(v1[0], v1[1]); w.w = cvt_pk_bf16(v1[2], v1[3]);
;                         *(u32x4*)(MG + row * D + col) = w; } } }
;     }
.LBB0_1647:
	v_add_u32_e32 v158, 0x90, v156
	v_mov_b64_e32 v[130:131], s[6:7]
	v_mad_i64_i32 v[130:131], s[2:3], v158, s13, v[130:131]
	v_lshl_add_u64 v[134:135], s[26:27], 1, v[130:131]
	v_lshl_add_u64 v[162:163], v[154:155], 1, v[134:135]
	s_mov_b64 s[100:101], 0x1e0000
	v_lshl_add_u64 v[248:249], v[230:231], 0, s[100:101]
	s_mov_b64 s[100:101], 0x1000
	v_lshl_add_u64 v[250:251], v[248:249], 0, s[100:101]
	global_load_dwordx4 v[180:183], v[248:249], off
	global_load_dwordx4 v[184:187], v[250:251], off
	global_load_dwordx4 v[188:191], v[248:249], off offset:256
	global_load_dwordx4 v[192:195], v[250:251], off offset:256
	s_nop 1
	s_and_b64 vcc, exec, s[44:45]
	v_lshl_add_u64 v[160:161], s[24:25], 1, v[130:131]
	s_waitcnt vmcnt(7)
	s_nop 1
	v_mov_b64_e32 v[176:177], v[196:197]
	v_mov_b64_e32 v[178:179], v[198:199]
	v_lshlrev_b32_e32 v168, 16, v176
	v_and_b32_e32 v169, 0xffff0000, v176
	v_lshlrev_b32_e32 v166, 16, v177
	v_and_b32_e32 v167, 0xffff0000, v177
	v_lshlrev_b32_e32 v170, 16, v178
	v_and_b32_e32 v171, 0xffff0000, v178
	v_lshlrev_b32_e32 v164, 16, v179
	v_and_b32_e32 v165, 0xffff0000, v179
	s_cbranch_vccnz .LBB0_1649
	v_lshl_add_u64 v[130:131], v[154:155], 1, v[160:161]
	s_nop 1
	s_waitcnt vmcnt(6)
	s_nop 1
	v_mov_b64_e32 v[176:177], v[200:201]
	v_mov_b64_e32 v[178:179], v[202:203]
	v_lshlrev_b32_e32 v130, 16, v176
	v_and_b32_e32 v131, 0xffff0000, v176
	v_max_f32_e32 v130, v130, v130
	v_max_f32_e32 v131, v131, v131
	v_max_f32_e32 v130, 0xda24260, v130
	v_max_f32_e32 v131, 0xda24260, v131
	v_rcp_f32_e32 v130, v130
	v_rcp_f32_e32 v131, v131
	v_lshlrev_b32_e32 v134, 16, v177
	v_and_b32_e32 v135, 0xffff0000, v177
	v_lshlrev_b32_e32 v140, 16, v178
	v_pk_mul_f32 v[168:169], v[130:131], v[168:169]
	v_max_f32_e32 v130, v134, v134
	v_max_f32_e32 v131, v135, v135
	v_max_f32_e32 v130, 0xda24260, v130
	v_max_f32_e32 v131, 0xda24260, v131
	v_rcp_f32_e32 v130, v130
	v_rcp_f32_e32 v131, v131
	v_and_b32_e32 v141, 0xffff0000, v178
	v_lshlrev_b32_e32 v142, 16, v179
	v_and_b32_e32 v143, 0xffff0000, v179
	v_pk_mul_f32 v[166:167], v[130:131], v[166:167]
	v_max_f32_e32 v130, v140, v140
	v_max_f32_e32 v131, v141, v141
	v_max_f32_e32 v130, 0xda24260, v130
	v_max_f32_e32 v131, 0xda24260, v131
	v_rcp_f32_e32 v130, v130
	v_rcp_f32_e32 v131, v131
	s_nop 0
	v_pk_mul_f32 v[170:171], v[130:131], v[170:171]
	v_max_f32_e32 v130, v142, v142
	v_max_f32_e32 v131, v143, v143
	v_max_f32_e32 v130, 0xda24260, v130
	v_max_f32_e32 v131, 0xda24260, v131
	v_rcp_f32_e32 v130, v130
	v_rcp_f32_e32 v131, v131
	s_nop 0
	v_pk_mul_f32 v[164:165], v[130:131], v[164:165]

; __device__ __forceinline__ unsigned cvt_pk_bf16(float lo, float hi) { unsigned r; asm volatile("v_cvt_pk_bf16_f32 %0, %1, %2" : "=v"(r) : "v"(lo), "v"(hi)); return r; }
;     __device__ __forceinline__ void operator()(f32x4 (&acc)[2][2][4][2], const Unit& u, int wr, int wc, int fr, int fq) const {
;         const int row0 = u.pm * BM + wr * 64 + fr; const int col0 = u.pn * BM + wc * 32 + 8 * fq; const int br = u.seg;
; #pragma unroll
;         for (int ai = 0; ai < 2; ++ai)
; #pragma unroll
;             for (int m = 0; m < 4; ++m) { const size_t row = (size_t)(row0 + ai * HALF + m * 16);
; #pragma unroll
;                 for (int bj = 0; bj < 2; ++bj) { const int col = col0 + bj * HALF;
;                     const u32x4 g = *(const u32x4*)(PG + row * 6144 + br * D + col);
;                     float s[8] = {bflo(g[0]), bfhi(g[0]), bflo(g[1]), bfhi(g[1]), bflo(g[2]), bfhi(g[2]), bflo(g[3]), bfhi(g[3])};
;                     if (br < 2) { const u32x4 h = *(const u32x4*)(PG + row * 6144 + (br + 1) * D + col);
;                         const float d[8] = {bflo(h[0]), bfhi(h[0]), bflo(h[1]), bfhi(h[1]), bflo(h[2]), bfhi(h[2]), bflo(h[3]), bfhi(h[3])};
; #pragma unroll
;                         for (int j = 0; j < 8; ++j) s[j] = s[j] * __builtin_amdgcn_rcpf(fmaxf(d[j], 1e-30f)); }
;                     f32x4& v0 = acc[ai][bj][m][0]; f32x4& v1 = acc[ai][bj][m][1];
; #pragma unroll
;                     for (int j = 0; j < 4; ++j) { v0[j] *= s[j]; v1[j] *= s[4 + j]; }
;                     if (br == 2) { u32x4 w; w.x = cvt_pk_bf16(v0[0], v0[1]); w.y = cvt_pk_bf16(v0[2], v0[3]); w.z = cvt_pk_bf16(v1[0], v1[1]); w.w = cvt_pk_bf16(v1[2], v1[3]);
;                         *(u32x4*)(MG + row * D + col) = w; } } }
;     }
.LBB0_1655:
	v_add_u32_e32 v158, 0xa0, v156
	v_mov_b64_e32 v[130:131], s[6:7]
	v_mad_i64_i32 v[130:131], s[2:3], v158, s13, v[130:131]
	v_lshl_add_u64 v[134:135], s[26:27], 1, v[130:131]
	v_lshl_add_u64 v[162:163], v[154:155], 1, v[134:135]
	s_mov_b64 s[100:101], 0x210000
	v_lshl_add_u64 v[248:249], v[230:231], 0, s[100:101]
	s_mov_b64 s[100:101], 0x1000
	v_lshl_add_u64 v[250:251], v[248:249], 0, s[100:101]
	global_load_dwordx4 v[196:199], v[248:249], off
	global_load_dwordx4 v[200:203], v[250:251], off
	global_load_dwordx4 v[204:207], v[248:249], off offset:256
	global_load_dwordx4 v[208:211], v[250:251], off offset:256
	s_nop 1
	s_and_b64 vcc, exec, s[44:45]
	v_lshl_add_u64 v[160:161], s[24:25], 1, v[130:131]
	s_waitcnt vmcnt(7)
	s_nop 1
	v_mov_b64_e32 v[176:177], v[180:181]
	v_mov_b64_e32 v[178:179], v[182:183]
	v_lshlrev_b32_e32 v168, 16, v176
	v_and_b32_e32 v169, 0xffff0000, v176
	v_lshlrev_b32_e32 v166, 16, v177
	v_and_b32_e32 v167, 0xffff0000, v177
	v_lshlrev_b32_e32 v170, 16, v178
	v_and_b32_e32 v171, 0xffff0000, v178
	v_lshlrev_b32_e32 v164, 16, v179
	v_and_b32_e32 v165, 0xffff0000, v179
	s_cbranch_vccnz .LBB0_1657
	v_lshl_add_u64 v[130:131], v[154:155], 1, v[160:161]
	s_nop 1
	s_waitcnt vmcnt(6)
	s_nop 1
	v_mov_b64_e32 v[176:177], v[184:185]
	v_mov_b64_e32 v[178:179], v[186:187]
	v_lshlrev_b32_e32 v130, 16, v176
	v_and_b32_e32 v131, 0xffff0000, v176
	v_max_f32_e32 v130, v130, v130
	v_max_f32_e32 v131, v131, v131
	v_max_f32_e32 v130, 0xda24260, v130
	v_max_f32_e32 v131, 0xda24260, v131
	v_rcp_f32_e32 v130, v130
	v_rcp_f32_e32 v131, v131
	v_lshlrev_b32_e32 v134, 16, v177
	v_and_b32_e32 v135, 0xffff0000, v177
	v_lshlrev_b32_e32 v140, 16, v178
	v_pk_mul_f32 v[168:169], v[130:131], v[168:169]
	v_max_f32_e32 v130, v134, v134
	v_max_f32_e32 v131, v135, v135
	v_max_f32_e32 v130, 0xda24260, v130
	v_max_f32_e32 v131, 0xda24260, v131
	v_rcp_f32_e32 v130, v130
	v_rcp_f32_e32 v131, v131
	v_and_b32_e32 v141, 0xffff0000, v178
	v_lshlrev_b32_e32 v142, 16, v179
	v_and_b32_e32 v143, 0xffff0000, v179
	v_pk_mul_f32 v[166:167], v[130:131], v[166:167]
	v_max_f32_e32 v130, v140, v140
	v_max_f32_e32 v131, v141, v141
	v_max_f32_e32 v130, 0xda24260, v130
	v_max_f32_e32 v131, 0xda24260, v131
	v_rcp_f32_e32 v130, v130
	v_rcp_f32_e32 v131, v131
	s_nop 0
	v_pk_mul_f32 v[170:171], v[130:131], v[170:171]
	v_max_f32_e32 v130, v142, v142
	v_max_f32_e32 v131, v143, v143
	v_max_f32_e32 v130, 0xda24260, v130
	v_max_f32_e32 v131, 0xda24260, v131
	v_rcp_f32_e32 v130, v130
	v_rcp_f32_e32 v131, v131
	s_nop 0
	v_pk_mul_f32 v[164:165], v[130:131], v[164:165]

; __device__ __forceinline__ unsigned cvt_pk_bf16(float lo, float hi) { unsigned r; asm volatile("v_cvt_pk_bf16_f32 %0, %1, %2" : "=v"(r) : "v"(lo), "v"(hi)); return r; }
;     __device__ __forceinline__ void operator()(f32x4 (&acc)[2][2][4][2], const Unit& u, int wr, int wc, int fr, int fq) const {
;         const int row0 = u.pm * BM + wr * 64 + fr; const int col0 = u.pn * BM + wc * 32 + 8 * fq; const int br = u.seg;
; #pragma unroll
;         for (int ai = 0; ai < 2; ++ai)
; #pragma unroll
;             for (int m = 0; m < 4; ++m) { const size_t row = (size_t)(row0 + ai * HALF + m * 16);
; #pragma unroll
;                 for (int bj = 0; bj < 2; ++bj) { const int col = col0 + bj * HALF;
;                     const u32x4 g = *(const u32x4*)(PG + row * 6144 + br * D + col);
;                     float s[8] = {bflo(g[0]), bfhi(g[0]), bflo(g[1]), bfhi(g[1]), bflo(g[2]), bfhi(g[2]), bflo(g[3]), bfhi(g[3])};
;                     if (br < 2) { const u32x4 h = *(const u32x4*)(PG + row * 6144 + (br + 1) * D + col);
;                         const float d[8] = {bflo(h[0]), bfhi(h[0]), bflo(h[1]), bfhi(h[1]), bflo(h[2]), bfhi(h[2]), bflo(h[3]), bfhi(h[3])};
; #pragma unroll
;                         for (int j = 0; j < 8; ++j) s[j] = s[j] * __builtin_amdgcn_rcpf(fmaxf(d[j], 1e-30f)); }
;                     f32x4& v0 = acc[ai][bj][m][0]; f32x4& v1 = acc[ai][bj][m][1];
; #pragma unroll
;                     for (int j = 0; j < 4; ++j) { v0[j] *= s[j]; v1[j] *= s[4 + j]; }
;                     if (br == 2) { u32x4 w; w.x = cvt_pk_bf16(v0[0], v0[1]); w.y = cvt_pk_bf16(v0[2], v0[3]); w.z = cvt_pk_bf16(v1[0], v1[1]); w.w = cvt_pk_bf16(v1[2], v1[3]);
;                         *(u32x4*)(MG + row * D + col) = w; } } }
;     }
.LBB0_1663:
	v_add_u32_e32 v156, 0xb0, v156
	v_mov_b64_e32 v[130:131], s[6:7]
	v_mad_i64_i32 v[130:131], s[2:3], v156, s13, v[130:131]
	v_lshl_add_u64 v[134:135], s[26:27], 1, v[130:131]
	v_lshl_add_u64 v[160:161], v[154:155], 1, v[134:135]
	s_nop 1
	s_and_b64 vcc, exec, s[44:45]
	v_lshl_add_u64 v[158:159], s[24:25], 1, v[130:131]
	s_waitcnt vmcnt(3)
	s_nop 1
	v_mov_b64_e32 v[168:169], v[196:197]
	v_mov_b64_e32 v[170:171], v[198:199]
	v_lshlrev_b32_e32 v166, 16, v168
	v_and_b32_e32 v167, 0xffff0000, v168
	v_lshlrev_b32_e32 v164, 16, v169
	v_and_b32_e32 v165, 0xffff0000, v169
	v_lshlrev_b32_e32 v168, 16, v170
	v_and_b32_e32 v169, 0xffff0000, v170
	v_lshlrev_b32_e32 v162, 16, v171
	v_and_b32_e32 v163, 0xffff0000, v171
	s_cbranch_vccnz .LBB0_1665
	v_lshl_add_u64 v[130:131], v[154:155], 1, v[158:159]
	s_nop 1
	s_waitcnt vmcnt(2)
	s_nop 1
	v_mov_b64_e32 v[176:177], v[200:201]
	v_mov_b64_e32 v[178:179], v[202:203]
	v_lshlrev_b32_e32 v130, 16, v176
	v_and_b32_e32 v131, 0xffff0000, v176
	v_max_f32_e32 v130, v130, v130
	v_max_f32_e32 v131, v131, v131
	v_max_f32_e32 v130, 0xda24260, v130
	v_max_f32_e32 v131, 0xda24260, v131
	v_rcp_f32_e32 v130, v130
	v_rcp_f32_e32 v131, v131
	v_lshlrev_b32_e32 v134, 16, v177
	v_and_b32_e32 v135, 0xffff0000, v177
	v_lshlrev_b32_e32 v140, 16, v178
	v_pk_mul_f32 v[166:167], v[130:131], v[166:167]
	v_max_f32_e32 v130, v134, v134
	v_max_f32_e32 v131, v135, v135
	v_max_f32_e32 v130, 0xda24260, v130
	v_max_f32_e32 v131, 0xda24260, v131
	v_rcp_f32_e32 v130, v130
	v_rcp_f32_e32 v131, v131
	v_and_b32_e32 v141, 0xffff0000, v178
	v_lshlrev_b32_e32 v142, 16, v179
	v_and_b32_e32 v143, 0xffff0000, v179
	v_pk_mul_f32 v[164:165], v[130:131], v[164:165]
	v_max_f32_e32 v130, v140, v140
	v_max_f32_e32 v131, v141, v141
	v_max_f32_e32 v130, 0xda24260, v130
	v_max_f32_e32 v131, 0xda24260, v131
	v_rcp_f32_e32 v130, v130
	v_rcp_f32_e32 v131, v131
	s_nop 0
	v_pk_mul_f32 v[168:169], v[130:131], v[168:169]
	v_max_f32_e32 v130, v142, v142
	v_max_f32_e32 v131, v143, v143
	v_max_f32_e32 v130, 0xda24260, v130
	v_max_f32_e32 v131, 0xda24260, v131
	v_rcp_f32_e32 v130, v130
	v_rcp_f32_e32 v131, v131
	s_nop 0
	v_pk_mul_f32 v[162:163], v[130:131], v[162:163]

; __device__ __forceinline__ unsigned cvt_pk_bf16(float lo, float hi) { unsigned r; asm volatile("v_cvt_pk_bf16_f32 %0, %1, %2" : "=v"(r) : "v"(lo), "v"(hi)); return r; }
;     __device__ __forceinline__ void operator()(f32x4 (&acc)[2][2][4][2], const Unit& u, int wr, int wc, int fr, int fq) const {
;         const int row0 = u.pm * BM + wr * 64 + fr; const int col0 = u.pn * BM + wc * 32 + 8 * fq; const int br = u.seg;
; #pragma unroll
;         for (int ai = 0; ai < 2; ++ai)
; #pragma unroll
;             for (int m = 0; m < 4; ++m) { const size_t row = (size_t)(row0 + ai * HALF + m * 16);
; #pragma unroll
;                 for (int bj = 0; bj < 2; ++bj) { const int col = col0 + bj * HALF;
;                     const u32x4 g = *(const u32x4*)(PG + row * 6144 + br * D + col);
;                     float s[8] = {bflo(g[0]), bfhi(g[0]), bflo(g[1]), bfhi(g[1]), bflo(g[2]), bfhi(g[2]), bflo(g[3]), bfhi(g[3])};
;                     if (br < 2) { const u32x4 h = *(const u32x4*)(PG + row * 6144 + (br + 1) * D + col);
;                         const float d[8] = {bflo(h[0]), bfhi(h[0]), bflo(h[1]), bfhi(h[1]), bflo(h[2]), bfhi(h[2]), bflo(h[3]), bfhi(h[3])};
; #pragma unroll
;                         for (int j = 0; j < 8; ++j) s[j] = s[j] * __builtin_amdgcn_rcpf(fmaxf(d[j], 1e-30f)); }
;                     f32x4& v0 = acc[ai][bj][m][0]; f32x4& v1 = acc[ai][bj][m][1];
; #pragma unroll
;                     for (int j = 0; j < 4; ++j) { v0[j] *= s[j]; v1[j] *= s[4 + j]; }
;                     if (br == 2) { u32x4 w; w.x = cvt_pk_bf16(v0[0], v0[1]); w.y = cvt_pk_bf16(v0[2], v0[3]); w.z = cvt_pk_bf16(v1[0], v1[1]); w.w = cvt_pk_bf16(v1[2], v1[3]);
;                         *(u32x4*)(MG + row * D + col) = w; } } }
;     }
.LBB0_1667:
	s_nop 1
	s_and_b64 vcc, exec, s[44:45]
	s_waitcnt vmcnt(0)
	s_nop 1
	v_mov_b64_e32 v[166:167], v[204:205]
	v_mov_b64_e32 v[168:169], v[206:207]
	v_lshlrev_b32_e32 v164, 16, v166
	v_and_b32_e32 v165, 0xffff0000, v166
	v_lshlrev_b32_e32 v162, 16, v167
	v_and_b32_e32 v163, 0xffff0000, v167
	v_lshlrev_b32_e32 v166, 16, v168
	v_and_b32_e32 v167, 0xffff0000, v168
	v_lshlrev_b32_e32 v160, 16, v169
	v_and_b32_e32 v161, 0xffff0000, v169
	s_cbranch_vccnz .LBB0_1669
	v_lshl_add_u64 v[130:131], v[154:155], 1, v[158:159]
	s_nop 1
	s_waitcnt vmcnt(0)
	s_nop 1
	v_mov_b64_e32 v[168:169], v[208:209]
	v_mov_b64_e32 v[170:171], v[210:211]
	v_lshlrev_b32_e32 v130, 16, v168
	v_and_b32_e32 v131, 0xffff0000, v168
	v_max_f32_e32 v130, v130, v130
	v_max_f32_e32 v131, v131, v131
	v_max_f32_e32 v130, 0xda24260, v130
	v_max_f32_e32 v131, 0xda24260, v131
	v_rcp_f32_e32 v130, v130
	v_rcp_f32_e32 v131, v131
	v_lshlrev_b32_e32 v134, 16, v169
	v_and_b32_e32 v135, 0xffff0000, v169
	v_lshlrev_b32_e32 v140, 16, v170
	v_pk_mul_f32 v[164:165], v[130:131], v[164:165]
	v_max_f32_e32 v130, v134, v134
	v_max_f32_e32 v131, v135, v135
	v_max_f32_e32 v130, 0xda24260, v130
	v_max_f32_e32 v131, 0xda24260, v131
	v_rcp_f32_e32 v130, v130
	v_rcp_f32_e32 v131, v131
	v_and_b32_e32 v141, 0xffff0000, v170
	v_lshlrev_b32_e32 v142, 16, v171
	v_and_b32_e32 v143, 0xffff0000, v171
	v_pk_mul_f32 v[162:163], v[130:131], v[162:163]
	v_max_f32_e32 v130, v140, v140
	v_max_f32_e32 v131, v141, v141
	v_max_f32_e32 v130, 0xda24260, v130
	v_max_f32_e32 v131, 0xda24260, v131
	v_rcp_f32_e32 v130, v130
	v_rcp_f32_e32 v131, v131
	s_nop 0
	v_pk_mul_f32 v[166:167], v[130:131], v[166:167]
	v_max_f32_e32 v130, v142, v142
	v_max_f32_e32 v131, v143, v143
	v_max_f32_e32 v130, 0xda24260, v130
	v_max_f32_e32 v131, 0xda24260, v131
	v_rcp_f32_e32 v130, v130
	v_rcp_f32_e32 v131, v131
	s_nop 0
	v_pk_mul_f32 v[160:161], v[130:131], v[160:161]
